# k61: k58 + nt on the attention unit's read-once Q and gate (ZA) loads
# speedup vs baseline: 1.0052x; 1.0052x over previous
; #define LAS __attribute__((address_space(3)))
; #define ATT_GLD16(dst, ptr) asm volatile("global_load_dwordx4 %0, %1, off" : "=&v"(dst) : "v"(ptr) : "memory")
; __device__ __forceinline__ void attn_unit(const UnitDesc& u, LAS unsigned char* shm, float qkmax, float thresh) {
;     ...
;     const int tid = tid_, lane = tid & 63, r32 = lane & 31, hi = lane >> 5; const int wid = __builtin_amdgcn_readfirstlane(tid >> 6);
;     const int NT = (u.q0 + u.nq) >> 6, nband = u.nq >> 6;
;     const bool active = wid * 32 < u.nq;
;     LAS float* wsf = (LAS float*)(shm + LDS_WS) + wid * 128;
;     const bf16_t* ksrc = u.K + (size_t)lane * 512 + wid * 8;
;     const bf16_t* vsrc = u.V + (size_t)(16 * (wid & 3) + (lane >> 2)) * 512 + (wid >> 2) * 32 + (lane & 3) * 8;
;     const float* lsrc = u.LF + (size_t)lane * 8;
;     LAS unsigned char* kdst = shm + LDS_K + wid * 1024 + lane * 16;
;     LAS unsigned char* vdst = shm + LDS_V + wid * 1024 + lane * 16;
;     const int vb0 = (int)(unsigned)(uintptr_t)(shm + LDS_V) + ((lane >> 4) & 1) * 32 + (lane & 3) * 8 + (4 * hi + ((lane & 15) >> 2)) * 64;
;     const LAS unsigned char* kb = shm + LDS_K + hi * 1024 + r32 * 16;
;     ...
;     u32x4 kreg = *(const u32x4*)(ksrc + (size_t)(NT - 1) * 64 * 512), vreg = *(const u32x4*)(vsrc + (size_t)(NT - 1) * 64 * 512);
;     float lfb[4];
; #pragma unroll
;     for (int jb = 0; jb < 4; ++jb) { const int tile = NT - 1 - jb; lfb[jb] = lsrc[(size_t)(tile > 0 ? tile : 0) * 64 * 8]; }
;     u32x4 kA, vA, kB, vB, kC, vC;
;     { const int t2 = NT >= 2 ? NT - 2 : 0, t3 = NT >= 3 ? NT - 3 : 0, t4 = NT >= 4 ? NT - 4 : 0;
;       ATT_GLD16(kA, ksrc + (size_t)t2 * 64 * 512); ATT_GLD16(vA, vsrc + (size_t)t2 * 64 * 512);
;       ATT_GLD16(kB, ksrc + (size_t)t3 * 64 * 512); ATT_GLD16(vB, vsrc + (size_t)t3 * 64 * 512);
;       ATT_GLD16(kC, ksrc + (size_t)t4 * 64 * 512); ATT_GLD16(vC, vsrc + (size_t)t4 * 64 * 512); }
;     bf16x8 qr[4];
; #pragma unroll
;     for (int d0 = 0; d0 < 4; ++d0) qr[d0] = (bf16x8){0, 0, 0, 0, 0, 0, 0, 0};
;     if (active) { const bf16_t* Qw = u.Q + (size_t)(wid * 32 + r32) * 512;
; #pragma unroll
;         for (int d0 = 0; d0 < 4; ++d0) qr[d0] = *(const bf16x8*)(Qw + d0 * 16 + hi * 8); }
.LBB0_731:
	s_lshl_b64 s[48:49], s[28:29], 2
	v_mov_b32_e32 v12, v208
	s_add_u32 s12, s12, s48
	s_addc_u32 s13, s13, s49
	v_and_b32_e32 v137, 63, v12
	v_cmp_gt_u32_e64 s[100:101], 16, v137
	s_nop 1
	v_cndmask_b32_e64 v191, 0, 1.0, s[100:101]
	v_cmp_gt_u32_e64 s[100:101], 32, v137
	s_nop 1
	v_cndmask_b32_e64 v192, 0, 1.0, s[100:101]
	v_cmp_gt_u32_e64 s[100:101], 48, v137
	s_nop 1
	v_cndmask_b32_e64 v193, 0, 1.0, s[100:101]
	v_readfirstlane_b32 s68, v12
	s_ashr_i32 s52, s68, 6
	v_lshlrev_b32_e32 v0, 10, v137
	v_lshl_add_u64 v[2:3], s[10:11], 0, v[0:1]
	s_lshl_b32 s10, s52, 3
	s_ashr_i32 s11, s10, 31
	v_lshl_add_u64 v[106:107], s[10:11], 1, v[2:3]
	s_lshl_b32 s10, s52, 4
	v_bfe_u32 v0, v12, 2, 4
	v_and_or_b32 v0, s10, 48, v0
	v_lshlrev_b32_e32 v0, 10, v0
	s_add_i32 s28, s53, s66
	v_lshl_add_u64 v[2:3], s[8:9], 0, v[0:1]
	s_ashr_i32 s8, s68, 3
	s_ashr_i32 s67, s28, 6
	s_andn2_b32 s8, s8, 31
	v_lshlrev_b32_e32 v138, 3, v12
	s_ashr_i32 s9, s8, 31
	v_and_b32_e32 v13, 24, v138
	s_add_i32 s48, s67, -1
	v_lshl_add_u64 v[2:3], s[8:9], 1, v[2:3]
	v_lshlrev_b32_e32 v0, 1, v13
	s_ashr_i32 s49, s48, 31
	v_lshl_add_u64 v[108:109], v[2:3], 0, v[0:1]
	v_lshlrev_b32_e32 v0, 5, v137
	s_lshl_b64 s[8:9], s[48:49], 16
	s_max_i32 s28, s48, 0
	v_lshl_add_u64 v[110:111], s[12:13], 0, v[0:1]
	v_lshl_add_u64 v[2:3], v[106:107], 0, s[8:9]
	v_lshl_add_u64 v[6:7], v[108:109], 0, s[8:9]
	s_lshl_b64 s[8:9], s[28:29], 11
	v_lshl_add_u64 v[10:11], v[110:111], 0, s[8:9]
	s_max_i32 s8, s67, 2
	s_add_i32 s28, s8, -2
	s_lshl_b64 s[8:9], s[28:29], 11
	v_lshl_add_u64 v[16:17], v[110:111], 0, s[8:9]
	s_max_i32 s8, s67, 3
	s_add_i32 s8, s8, -3
	s_mov_b32 s9, s29
	s_lshl_b64 s[10:11], s[8:9], 11
	v_lshl_add_u64 v[18:19], v[110:111], 0, s[10:11]
	s_max_i32 s10, s67, 4
	s_add_i32 s10, s10, -4
	s_mov_b32 s11, s29
	s_lshl_b64 s[12:13], s[10:11], 11
	v_lshl_add_u64 v[20:21], v[110:111], 0, s[12:13]
	global_load_dword v14, v[10:11], off
	global_load_dword v140, v[16:17], off
	global_load_dword v141, v[18:19], off
	global_load_dword v139, v[20:21], off
	global_load_dwordx4 v[2:5], v[2:3], off
	global_load_dwordx4 v[6:9], v[6:7], off
	s_lshl_b32 s49, s52, 5
	s_cmp_lt_i32 s49, s53
	s_cselect_b64 s[58:59], -1, 0
	s_cmp_ge_i32 s49, s53
	s_cselect_b64 s[60:61], -1, 0
	v_and_b32_e32 v135, 31, v12
	v_bfe_u32 v136, v12, 5, 1
	s_and_b64 vcc, exec, s[60:61]
	v_or_b32_e32 v10, s49, v135
	s_cbranch_vccnz .LBB0_733
	v_ashrrev_i32_e32 v11, 31, v10
	v_lshlrev_b64 v[16:17], 10, v[10:11]
	v_lshl_add_u64 v[16:17], s[6:7], 0, v[16:17]
	v_lshlrev_b32_e32 v0, 4, v136
	v_lshl_add_u64 v[16:17], v[16:17], 0, v[0:1]
	global_load_dwordx4 v[94:97], v[16:17], off nt
	global_load_dwordx4 v[98:101], v[16:17], off offset:32 nt
	global_load_dwordx4 v[102:105], v[16:17], off offset:64 nt
	global_load_dwordx4 v[90:93], v[16:17], off offset:96 nt
	s_branch .LBB0_734

; #define LAS __attribute__((address_space(3)))
; __device__ __forceinline__ void attn_unit(const UnitDesc& u, LAS unsigned char* shm, float qkmax, float thresh) {
;     ...
;     asm volatile("s_waitcnt vmcnt(0)" : "+v"(kA), "+v"(vA), "+v"(kB), "+v"(vB), "+v"(kC), "+v"(vC), "+v"(lA), "+v"(lB), "+v"(lC) :: "memory");
;     if (active) {
;         u32x4 zv4[4];
; #pragma unroll
;         for (int i = 0; i < 4; ++i) zv4[i] = *(const u32x4*)(u.Zg + (size_t)(wid * 32 + i * 8 + (lane >> 3)) * 512 + (lane & 7) * 8);
;         { auto rr = __builtin_amdgcn_permlane32_swap(__float_as_uint(l_reg), __float_as_uint(l_reg), false, false); l_reg = __uint_as_float(rr[0]) + __uint_as_float(rr[1]); }
;         LAS float* lx = (LAS float*)(shm + LDS_LX) + wid * 32;
;         if (hi == 0) lx[r32] = l_reg;
.LBB0_829:
	s_or_b64 exec, exec, s[62:63]
	s_nop 0
	s_and_b64 vcc, exec, s[12:13]
	s_cbranch_vccnz .LBB0_719
	s_nop 7
	s_nop 7
	v_mov_b64_e32 v[34:35], v[2:3]
	v_mov_b64_e32 v[36:37], v[4:5]
	v_mov_b64_e32 v[38:39], v[6:7]
	v_mov_b64_e32 v[40:41], v[8:9]
	v_mov_b64_e32 v[42:43], v[10:11]
	v_mov_b64_e32 v[44:45], v[12:13]
	v_mov_b64_e32 v[46:47], v[14:15]
	v_mov_b64_e32 v[48:49], v[16:17]
	v_mov_b64_e32 v[50:51], v[18:19]
	v_mov_b64_e32 v[52:53], v[20:21]
	v_mov_b64_e32 v[54:55], v[22:23]
	v_mov_b64_e32 v[56:57], v[24:25]
	v_mov_b64_e32 v[58:59], v[26:27]
	v_mov_b64_e32 v[60:61], v[28:29]
	v_mov_b64_e32 v[62:63], v[30:31]
	v_mov_b64_e32 v[64:65], v[32:33]
	s_lshl_b64 s[6:7], s[44:45], 1
	s_add_u32 s8, s24, s6
	v_lshrrev_b32_e32 v20, 3, v137
	s_addc_u32 s9, s25, s7
	s_lshl_b64 s[6:7], s[46:47], 1
	v_or_b32_e32 v18, s49, v20
	s_add_u32 s8, s8, s6
	v_and_b32_e32 v0, 56, v138
	v_or_b32_e32 v6, 8, v18
	s_addc_u32 s9, s9, s7
	v_lshlrev_b32_e32 v0, 1, v0
	v_ashrrev_i32_e32 v19, 31, v18
	v_ashrrev_i32_e32 v7, 31, v6
	v_lshl_add_u64 v[2:3], s[8:9], 0, v[0:1]
	v_lshlrev_b64 v[4:5], 10, v[18:19]
	v_lshlrev_b64 v[6:7], 10, v[6:7]
	v_lshl_add_u64 v[4:5], v[2:3], 0, v[4:5]
	v_lshl_add_u64 v[6:7], v[2:3], 0, v[6:7]
	global_load_dwordx4 v[14:17], v[4:5], off nt
	global_load_dwordx4 v[10:13], v[6:7], off nt
	v_or_b32_e32 v4, 16, v18
	v_or_b32_e32 v6, 24, v18
	v_ashrrev_i32_e32 v5, 31, v4
	v_ashrrev_i32_e32 v7, 31, v6
	v_lshlrev_b64 v[4:5], 10, v[4:5]
	v_lshlrev_b64 v[6:7], 10, v[6:7]
	v_lshl_add_u64 v[4:5], v[2:3], 0, v[4:5]
	v_lshl_add_u64 v[2:3], v[2:3], 0, v[6:7]
	global_load_dwordx4 v[6:9], v[4:5], off nt
	s_nop 0
	global_load_dwordx4 v[2:5], v[2:3], off nt
	v_mov_b32_e32 v21, v148
	s_lshl_b32 s8, s49, 2
	s_nop 0
	v_permlane32_swap_b32_e32 v148, v21
	s_add_i32 s10, s8, 0
	v_cmp_gt_u32_e32 vcc, 32, v137
	s_and_saveexec_b64 s[8:9], vcc
	s_cbranch_execz .LBB0_718
	v_add_f32_e32 v21, v148, v21
	v_lshl_add_u32 v22, v135, 2, s10
	ds_write_b32 v22, v21 offset:36864
	s_branch .LBB0_718
